# P4 router GEMV: the thread's 64 loop-invariant router weights loaded once per phase into registers; K loop unrolled over them (was 16 serialized reload+wait round trips per 8-row group)
# speedup vs baseline: 1.0218x; 1.0078x over previous
; __device__ __forceinline__ void router_rows(const Params& p, char* smem, int l, int nrows) {
;     ...
;   const float* XR = l == 0 ? (const float*)(ws + OFF_XNEW) : p.out;
;   u16* H2 = (u16*)(ws + OFF_H2);
;   const float* nw = p.norm2_w + l * 1024;
;   const float* wr = p.w_router + (size_t)l * 1024 * 16;
;   float* Hs = (float*)smem;
;   float* red = Hs + 256 * 36;
;   const int ngroups = nrows >> 3;
;   for (int grp = blockIdx.x; grp < ngroups; grp += gridDim.x) {
.LBB0_1267:
	s_or_b64 exec, exec, s[0:1]
	v_readlane_b32 s0, v237, 29
	v_readlane_b32 s1, v237, 30
	s_and_b64 s[0:1], s[0:1], exec
	s_movk_i32 s0, 0x840
	s_cselect_b32 s2, s0, 0x800
	v_readlane_b32 s0, v239, 0
	s_cmp_lt_i32 s0, s2
	v_mov_b32_e32 v2, v172
	s_mov_b64 s[4:5], s[58:59]
	v_readlane_b32 s0, v239, 63
	s_waitcnt lgkmcnt(0)
	s_barrier
	v_readlane_b32 s1, v238, 0
	s_cbranch_scc0 .LBB0_1279
; #define LAUNDER(v) asm volatile("" : "+s"(v))
; __device__ __forceinline__ int vtid() { int t = threadIdx.x; asm volatile("" : "+v"(t)); return t; }
; __device__ __forceinline__ void router_rows(const Params& p, char* smem, int l, int nrows) {
;   const int tid = vtid(), lane = tid & 63, wid = tid >> 6;
;   char* ws = p.ws;
;   LAUNDER(ws); LAUNDER(l);
;   const float* XR = l == 0 ? (const float*)(ws + OFF_XNEW) : p.out;
;   u16* H2 = (u16*)(ws + OFF_H2);
;   const float* nw = p.norm2_w + l * 1024;
;   const float* wr = p.w_router + (size_t)l * 1024 * 16;
;   float* Hs = (float*)smem;
;   float* red = Hs + 256 * 36;
;   const int ngroups = nrows >> 3;
;     ...
;       const int e = tid & 15, ks = tid >> 4;
;       float acc[8];
; #pragma unroll
;       for (int r = 0; r < 8; ++r) acc[r] = 0.f;
;       const float* wp = wr + (size_t)(ks * 64) * 16 + e;
;       const float* hp = Hs + (ks * 16) * 36;
; #pragma unroll 2
;       for (int kg = 0; kg < 16; ++kg) {
;         const float w0 = wp[(kg * 4 + 0) * 16], w1 = wp[(kg * 4 + 1) * 16], w2 = wp[(kg * 4 + 2) * 16], w3 = wp[(kg * 4 + 3) * 16];
	v_and_b32_e32 v0, 64, v173
	v_add_u32_e32 v0, 64, v0
	v_xor_b32_e32 v3, 32, v173
	v_cmp_lt_i32_e32 vcc, v3, v0
	s_add_u32 s1, s4, 0x2a196100
	s_addc_u32 s6, s5, 0
	v_cndmask_b32_e32 v3, v173, v3, vcc
	s_waitcnt vmcnt(0)
	v_lshlrev_b32_e32 v52, 2, v3
	v_xor_b32_e32 v3, 16, v173
	v_cmp_lt_i32_e32 vcc, v3, v0
	s_cmp_eq_u32 s0, 0
	v_readlane_b32 s12, v239, 7
	v_cndmask_b32_e32 v3, v173, v3, vcc
	v_lshlrev_b32_e32 v53, 2, v3
	v_xor_b32_e32 v3, 8, v173
	v_cmp_lt_i32_e32 vcc, v3, v0
	s_cselect_b32 s7, s6, s57
	s_cselect_b32 s6, s1, s56
	v_cndmask_b32_e32 v3, v173, v3, vcc
	v_lshlrev_b32_e32 v54, 2, v3
	v_xor_b32_e32 v3, 4, v173
	v_cmp_lt_i32_e32 vcc, v3, v0
	s_lshl_b32 s8, s0, 10
	v_readlane_b32 s13, v239, 8
	v_readlane_b32 s14, v239, 9
	v_readlane_b32 s15, v239, 10
	v_readlane_b32 s24, v239, 19
	v_readlane_b32 s25, v239, 20
	v_cndmask_b32_e32 v3, v173, v3, vcc
	s_ashr_i32 s9, s8, 31
	v_readlane_b32 s26, v239, 21
	v_readlane_b32 s27, v239, 22
	s_mov_b64 s[12:13], s[24:25]
	v_lshlrev_b32_e32 v55, 2, v3
	v_xor_b32_e32 v3, 2, v173
	s_lshl_b64 s[8:9], s[8:9], 2
	s_mov_b64 s[14:15], s[26:27]
	v_cmp_lt_i32_e32 vcc, v3, v0
	s_add_u32 s10, s14, s8
	v_readlane_b32 s16, v239, 11
	v_cndmask_b32_e32 v3, v173, v3, vcc
	v_readlane_b32 s17, v239, 12
	v_readlane_b32 s18, v239, 13
	v_readlane_b32 s19, v239, 14
	s_addc_u32 s11, s15, s9
	s_ashr_i32 s1, s0, 31
	v_lshlrev_b32_e32 v56, 2, v3
	v_xor_b32_e32 v3, 1, v173
	s_lshl_b64 s[8:9], s[0:1], 16
	v_readlane_b32 s12, v238, 25
	v_cmp_lt_i32_e32 vcc, v3, v0
	s_add_u32 s12, s12, s8
	s_mul_i32 s8, s0, 3
	v_cndmask_b32_e32 v0, v173, v3, vcc
	v_and_b32_e32 v3, -16, v2
	s_movk_i32 s0, 0x90
	v_lshlrev_b32_e32 v57, 2, v0
	v_ashrrev_i32_e32 v59, 4, v2
	v_mul_lo_u32 v0, v3, s0
	s_movk_i32 s0, 0x80
	v_and_b32_e32 v58, 15, v2
	v_lshlrev_b32_e32 v4, 6, v59
	v_cmp_gt_i32_e64 s[40:41], s0, v2
	s_movk_i32 s0, 0xff74
	v_and_b32_e32 v8, 63, v2
	v_readlane_b32 s13, v238, 26
	v_ashrrev_i32_e32 v10, 6, v2
	v_ashrrev_i32_e32 v5, 31, v4
	v_lshlrev_b32_e32 v6, 2, v58
	v_lshlrev_b32_e32 v60, 2, v2
	v_mad_u64_u32 v[2:3], s[0:1], v3, s0, v[0:1]
	s_addc_u32 s13, s13, s9
	v_lshlrev_b64 v[4:5], 6, v[4:5]
	v_or_b32_e32 v61, v2, v6
	v_lshlrev_b32_e32 v2, 15, v58
	v_mov_b32_e32 v3, v1
	v_lshl_add_u64 v[4:5], s[12:13], 0, v[4:5]
	v_lshl_add_u64 v[2:3], s[4:5], 0, v[2:3]
	s_mov_b64 s[12:13], 0x2e396100
	v_mov_b32_e32 v7, v1
	v_lshl_add_u64 v[16:17], v[2:3], 0, s[12:13]
	v_lshlrev_b32_e32 v2, 4, v8
	v_mov_b32_e32 v3, v1
	v_lshl_add_u64 v[14:15], v[4:5], 0, v[6:7]
	global_load_dword v80, v[14:15], off
	global_load_dword v81, v[14:15], off offset:64
	global_load_dword v82, v[14:15], off offset:128
	global_load_dword v83, v[14:15], off offset:192
	global_load_dword v84, v[14:15], off offset:256
	global_load_dword v85, v[14:15], off offset:320
	global_load_dword v86, v[14:15], off offset:384
	global_load_dword v87, v[14:15], off offset:448
	global_load_dword v88, v[14:15], off offset:512
	global_load_dword v89, v[14:15], off offset:576
	global_load_dword v90, v[14:15], off offset:640
	global_load_dword v91, v[14:15], off offset:704
	global_load_dword v92, v[14:15], off offset:768
	global_load_dword v93, v[14:15], off offset:832
	global_load_dword v94, v[14:15], off offset:896
	global_load_dword v95, v[14:15], off offset:960
	global_load_dword v96, v[14:15], off offset:1024
	global_load_dword v97, v[14:15], off offset:1088
	global_load_dword v98, v[14:15], off offset:1152
	global_load_dword v99, v[14:15], off offset:1216
	global_load_dword v100, v[14:15], off offset:1280
	global_load_dword v101, v[14:15], off offset:1344
	global_load_dword v102, v[14:15], off offset:1408
	global_load_dword v103, v[14:15], off offset:1472
	global_load_dword v104, v[14:15], off offset:1536
	global_load_dword v105, v[14:15], off offset:1600
	global_load_dword v106, v[14:15], off offset:1664
	global_load_dword v107, v[14:15], off offset:1728
	global_load_dword v108, v[14:15], off offset:1792
	global_load_dword v109, v[14:15], off offset:1856
	global_load_dword v110, v[14:15], off offset:1920
	global_load_dword v111, v[14:15], off offset:1984
	global_load_dword v112, v[14:15], off offset:2048
	global_load_dword v113, v[14:15], off offset:2112
	global_load_dword v114, v[14:15], off offset:2176
	global_load_dword v115, v[14:15], off offset:2240
	global_load_dword v116, v[14:15], off offset:2304
	global_load_dword v117, v[14:15], off offset:2368
	global_load_dword v118, v[14:15], off offset:2432
	global_load_dword v119, v[14:15], off offset:2496
	global_load_dword v120, v[14:15], off offset:2560
	global_load_dword v121, v[14:15], off offset:2624
	global_load_dword v122, v[14:15], off offset:2688
	global_load_dword v123, v[14:15], off offset:2752
	global_load_dword v124, v[14:15], off offset:2816
	global_load_dword v125, v[14:15], off offset:2880
	global_load_dword v126, v[14:15], off offset:2944
	global_load_dword v127, v[14:15], off offset:3008
	global_load_dword v128, v[14:15], off offset:3072
	global_load_dword v129, v[14:15], off offset:3136
	global_load_dword v130, v[14:15], off offset:3200
	global_load_dword v131, v[14:15], off offset:3264
	global_load_dword v132, v[14:15], off offset:3328
	global_load_dword v133, v[14:15], off offset:3392
	global_load_dword v134, v[14:15], off offset:3456
	global_load_dword v135, v[14:15], off offset:3520
	global_load_dword v136, v[14:15], off offset:3584
	global_load_dword v137, v[14:15], off offset:3648
	global_load_dword v138, v[14:15], off offset:3712
	global_load_dword v139, v[14:15], off offset:3776
	global_load_dword v140, v[14:15], off offset:3840
	global_load_dword v141, v[14:15], off offset:3904
	global_load_dword v142, v[14:15], off offset:3968
	global_load_dword v143, v[14:15], off offset:4032
	v_lshl_add_u64 v[18:19], s[10:11], 0, v[2:3]
	v_or_b32_e32 v5, 64, v8
	v_lshl_add_u64 v[20:21], s[6:7], 0, v[2:3]
	v_lshl_add_u64 v[2:3], s[4:5], 0, v[2:3]
	s_mov_b64 s[6:7], 0x18e00000
	v_lshlrev_b32_e32 v33, 1, v10
	s_add_u32 s0, s4, 0x2e496100
	v_mul_u32_u24_e32 v64, 0x90, v5
	v_or_b32_e32 v5, 0x80, v8
	v_lshl_add_u64 v[22:23], v[2:3], 0, s[6:7]
	v_lshlrev_b32_e32 v2, 3, v8
	v_mov_b32_e32 v3, v1
	v_lshlrev_b32_e32 v9, 2, v8
	v_lshlrev_b32_e32 v4, 9, v10
	s_addc_u32 s1, s5, 0
	v_mul_u32_u24_e32 v65, 0x90, v5
	v_or_b32_e32 v5, 0xc0, v8
	v_or_b32_e32 v67, 1, v33
	v_lshl_add_u64 v[2:3], s[4:5], 0, v[2:3]
	s_mov_b64 s[4:5], 0x1d3d6100
	v_cmp_gt_u32_e64 s[38:39], 16, v8
	v_lshlrev_b32_e32 v62, 5, v10
	v_mul_u32_u24_e32 v63, 0x90, v8
	v_mul_u32_u24_e32 v66, 0x90, v5
	v_lshlrev_b32_e32 v68, 4, v67
	v_lshl_add_u64 v[24:25], v[2:3], 0, s[4:5]
	v_add_u32_e32 v69, v9, v4
	v_readlane_b32 s9, v239, 0
	v_readlane_b32 s20, v239, 15
	v_readlane_b32 s21, v239, 16
	v_readlane_b32 s22, v239, 17
	v_readlane_b32 s23, v239, 18
	v_readlane_b32 s14, v238, 27
	v_readlane_b32 s15, v238, 28
	v_readlane_b32 s16, v238, 29
	v_readlane_b32 s17, v238, 30
	v_readlane_b32 s18, v238, 31
	v_readlane_b32 s19, v238, 32
	s_branch .LBB0_1270

; __device__ __forceinline__ void router_rows(const Params& p, char* smem, int l, int nrows) {
;     ...
;       for (int kg = 0; kg < 16; ++kg) {
;         const float w0 = wp[(kg * 4 + 0) * 16], w1 = wp[(kg * 4 + 1) * 16], w2 = wp[(kg * 4 + 2) * 16], w3 = wp[(kg * 4 + 3) * 16];
; #pragma unroll
;         for (int r = 0; r < 8; ++r) {
;           const float4 hv = *(const float4*)&hp[kg * 36 + r * 4];
;           acc[r] += hv.x * w0 + hv.y * w1 + hv.z * w2 + hv.w * w3;
;         }
;       }
.LBB0_1271:
	v_mov_b32_e32 v30, v80
	v_mov_b32_e32 v31, v81
	v_mov_b32_e32 v50, v82
	v_mov_b32_e32 v51, v83
	ds_read_b128 v[26:29], v10 offset:96
	ds_read_b128 v[34:37], v10 offset:112
	ds_read_b128 v[38:41], v10
	ds_read_b128 v[42:45], v10 offset:16
	ds_read_b128 v[46:49], v10 offset:32
	ds_read_b128 v[70:73], v10 offset:48
	s_add_u32 s4, s4, 0x200
	s_waitcnt lgkmcnt(0)
	v_mov_b32_e32 v76, v38
	v_mov_b32_e32 v77, v42
	v_mov_b32_e32 v42, v39
	v_mov_b32_e32 v38, v40
	v_mov_b32_e32 v39, v44
	v_mov_b32_e32 v44, v41
	s_addc_u32 s5, s5, 0
	v_mul_f32_e32 v26, v30, v26
	v_mov_b32_e32 v32, v31
	v_pk_mul_f32 v[40:41], v[32:33], v[42:43] op_sel_hi:[0,1]
	v_pk_fma_f32 v[40:41], v[30:31], v[76:77], v[40:41] op_sel_hi:[0,1,1]
	v_pk_fma_f32 v[38:39], v[50:51], v[38:39], v[40:41] op_sel_hi:[0,1,1]
	v_mov_b32_e32 v76, v51
	v_pk_fma_f32 v[38:39], v[76:77], v[44:45], v[38:39] op_sel_hi:[0,1,1]
	v_pk_add_f32 v[6:7], v[6:7], v[38:39]
	v_mov_b32_e32 v39, v70
	v_mov_b32_e32 v70, v47
	v_mov_b32_e32 v38, v46
	v_pk_mul_f32 v[42:43], v[32:33], v[70:71] op_sel_hi:[0,1]
	v_mov_b32_e32 v40, v48
	v_mov_b32_e32 v41, v72
	v_pk_fma_f32 v[38:39], v[30:31], v[38:39], v[42:43] op_sel_hi:[0,1,1]
	v_mov_b32_e32 v72, v49
	v_pk_fma_f32 v[38:39], v[50:51], v[40:41], v[38:39] op_sel_hi:[0,1,1]
	v_pk_fma_f32 v[38:39], v[76:77], v[72:73], v[38:39] op_sel_hi:[0,1,1]
	v_pk_add_f32 v[8:9], v[8:9], v[38:39]
	ds_read_b128 v[38:41], v10 offset:80
	ds_read_b128 v[42:45], v10 offset:64
	v_mul_f32_e32 v74, v31, v27
	v_pk_mul_f32 v[34:35], v[30:31], v[34:35]
	v_pk_mul_f32 v[36:37], v[50:51], v[36:37]
	s_waitcnt lgkmcnt(1)
	v_mov_b32_e32 v47, v38
	s_waitcnt lgkmcnt(0)
	v_mov_b32_e32 v38, v43
	v_mov_b32_e32 v46, v42
	v_pk_mul_f32 v[38:39], v[32:33], v[38:39] op_sel_hi:[0,1]
	v_mov_b32_e32 v42, v44
	v_mov_b32_e32 v43, v40
	v_pk_fma_f32 v[30:31], v[30:31], v[46:47], v[38:39] op_sel_hi:[0,1,1]
	v_mov_b32_e32 v40, v45
	v_pk_fma_f32 v[30:31], v[50:51], v[42:43], v[30:31] op_sel_hi:[0,1,1]
	v_pk_fma_f32 v[30:31], v[76:77], v[40:41], v[30:31] op_sel_hi:[0,1,1]
	v_mov_b32_e32 v27, v34
	v_mov_b32_e32 v75, v35
	v_pk_add_f32 v[4:5], v[4:5], v[30:31]
	v_mul_f32_e32 v28, v50, v28
	v_mul_f32_e32 v30, v51, v29
	v_pk_add_f32 v[26:27], v[26:27], v[74:75]
	v_mov_b32_e32 v29, v36
	v_pk_add_f32 v[26:27], v[26:27], v[28:29]
	v_mov_b32_e32 v31, v37
	v_pk_add_f32 v[26:27], v[26:27], v[30:31]
	v_mov_b32_e32 v30, v84
	v_mov_b32_e32 v31, v85
	v_mov_b32_e32 v46, v86
	v_mov_b32_e32 v47, v87
	v_pk_add_f32 v[2:3], v[2:3], v[26:27]
	ds_read_b128 v[26:29], v10 offset:240
	ds_read_b128 v[34:37], v10 offset:256
	ds_read_b128 v[38:41], v10 offset:160
	ds_read_b128 v[42:45], v10 offset:144
	s_waitcnt lgkmcnt(1)
	v_mov_b32_e32 v49, v38
	s_waitcnt lgkmcnt(0)
	v_mov_b32_e32 v38, v43
	v_mov_b32_e32 v48, v42
	v_mov_b32_e32 v42, v44
	v_mov_b32_e32 v43, v40
	v_mov_b32_e32 v40, v45
	v_mul_f32_e32 v12, v30, v26
	v_mov_b32_e32 v32, v31
	v_pk_mul_f32 v[38:39], v[32:33], v[38:39] op_sel_hi:[0,1]
	v_pk_fma_f32 v[38:39], v[30:31], v[48:49], v[38:39] op_sel_hi:[0,1,1]
	v_pk_fma_f32 v[38:39], v[46:47], v[42:43], v[38:39] op_sel_hi:[0,1,1]
	v_mov_b32_e32 v48, v47
	v_pk_fma_f32 v[38:39], v[48:49], v[40:41], v[38:39] op_sel_hi:[0,1,1]
	v_pk_add_f32 v[6:7], v[6:7], v[38:39]
	ds_read_b128 v[38:41], v10 offset:192
	ds_read_b128 v[42:45], v10 offset:176
	v_mul_f32_e32 v26, v31, v27
	v_pk_mul_f32 v[34:35], v[30:31], v[34:35]
	v_pk_mul_f32 v[36:37], v[46:47], v[36:37]
	s_waitcnt lgkmcnt(1)
	v_mov_b32_e32 v51, v38
	s_waitcnt lgkmcnt(0)
	v_mov_b32_e32 v38, v43
	v_mov_b32_e32 v50, v42
	v_pk_mul_f32 v[38:39], v[32:33], v[38:39] op_sel_hi:[0,1]
	v_mov_b32_e32 v42, v44
	v_mov_b32_e32 v43, v40
	v_pk_fma_f32 v[38:39], v[30:31], v[50:51], v[38:39] op_sel_hi:[0,1,1]
	v_mov_b32_e32 v40, v45
	v_pk_fma_f32 v[38:39], v[46:47], v[42:43], v[38:39] op_sel_hi:[0,1,1]
	v_pk_fma_f32 v[38:39], v[48:49], v[40:41], v[38:39] op_sel_hi:[0,1,1]
	v_pk_add_f32 v[8:9], v[8:9], v[38:39]
	ds_read_b128 v[38:41], v10 offset:224
	ds_read_b128 v[42:45], v10 offset:208
	v_mov_b32_e32 v13, v34
	v_mov_b32_e32 v27, v35
	v_mul_f32_e32 v28, v46, v28
	s_waitcnt lgkmcnt(1)
	v_mov_b32_e32 v51, v38
	s_waitcnt lgkmcnt(0)
	v_mov_b32_e32 v38, v43
	v_mov_b32_e32 v50, v42
	v_pk_mul_f32 v[38:39], v[32:33], v[38:39] op_sel_hi:[0,1]
	v_mov_b32_e32 v42, v44
	v_mov_b32_e32 v43, v40
	v_pk_fma_f32 v[30:31], v[30:31], v[50:51], v[38:39] op_sel_hi:[0,1,1]
	v_mov_b32_e32 v40, v45
	v_pk_fma_f32 v[30:31], v[46:47], v[42:43], v[30:31] op_sel_hi:[0,1,1]
	v_pk_fma_f32 v[30:31], v[48:49], v[40:41], v[30:31] op_sel_hi:[0,1,1]
	v_pk_add_f32 v[4:5], v[4:5], v[30:31]
	v_mul_f32_e32 v30, v47, v29
	v_pk_add_f32 v[12:13], v[12:13], v[26:27]
	v_mov_b32_e32 v29, v36
	v_pk_add_f32 v[12:13], v[12:13], v[28:29]
	v_mov_b32_e32 v31, v37
	v_pk_add_f32 v[12:13], v[12:13], v[30:31]
	v_add_u32_e32 v10, 0x120, v10
	v_pk_add_f32 v[2:3], v[2:3], v[12:13]
	v_mov_b32_e32 v30, v88
	v_mov_b32_e32 v31, v89
	v_mov_b32_e32 v50, v90
	v_mov_b32_e32 v51, v91
	ds_read_b128 v[26:29], v10 offset:96
	ds_read_b128 v[34:37], v10 offset:112
	ds_read_b128 v[38:41], v10
	ds_read_b128 v[42:45], v10 offset:16
	ds_read_b128 v[46:49], v10 offset:32
	ds_read_b128 v[70:73], v10 offset:48
	s_add_u32 s4, s4, 0x200
	s_waitcnt lgkmcnt(0)
; __device__ __forceinline__ void router_rows(const Params& p, char* smem, int l, int nrows) {
;     ...
;       for (int kg = 0; kg < 16; ++kg) {
;         const float w0 = wp[(kg * 4 + 0) * 16], w1 = wp[(kg * 4 + 1) * 16], w2 = wp[(kg * 4 + 2) * 16], w3 = wp[(kg * 4 + 3) * 16];
; #pragma unroll
;         for (int r = 0; r < 8; ++r) {
;           const float4 hv = *(const float4*)&hp[kg * 36 + r * 4];
;           acc[r] += hv.x * w0 + hv.y * w1 + hv.z * w2 + hv.w * w3;
;         }
;       }
	v_mov_b32_e32 v76, v38
	v_mov_b32_e32 v77, v42
	v_mov_b32_e32 v42, v39
	v_mov_b32_e32 v38, v40
	v_mov_b32_e32 v39, v44
	v_mov_b32_e32 v44, v41
	s_addc_u32 s5, s5, 0
	v_mul_f32_e32 v26, v30, v26
	v_mov_b32_e32 v32, v31
	v_pk_mul_f32 v[40:41], v[32:33], v[42:43] op_sel_hi:[0,1]
	v_pk_fma_f32 v[40:41], v[30:31], v[76:77], v[40:41] op_sel_hi:[0,1,1]
	v_pk_fma_f32 v[38:39], v[50:51], v[38:39], v[40:41] op_sel_hi:[0,1,1]
	v_mov_b32_e32 v76, v51
	v_pk_fma_f32 v[38:39], v[76:77], v[44:45], v[38:39] op_sel_hi:[0,1,1]
	v_pk_add_f32 v[6:7], v[6:7], v[38:39]
	v_mov_b32_e32 v39, v70
	v_mov_b32_e32 v70, v47
	v_mov_b32_e32 v38, v46
	v_pk_mul_f32 v[42:43], v[32:33], v[70:71] op_sel_hi:[0,1]
	v_mov_b32_e32 v40, v48
	v_mov_b32_e32 v41, v72
	v_pk_fma_f32 v[38:39], v[30:31], v[38:39], v[42:43] op_sel_hi:[0,1,1]
	v_mov_b32_e32 v72, v49
	v_pk_fma_f32 v[38:39], v[50:51], v[40:41], v[38:39] op_sel_hi:[0,1,1]
	v_pk_fma_f32 v[38:39], v[76:77], v[72:73], v[38:39] op_sel_hi:[0,1,1]
	v_pk_add_f32 v[8:9], v[8:9], v[38:39]
	ds_read_b128 v[38:41], v10 offset:80
	ds_read_b128 v[42:45], v10 offset:64
	v_mul_f32_e32 v74, v31, v27
	v_pk_mul_f32 v[34:35], v[30:31], v[34:35]
	v_pk_mul_f32 v[36:37], v[50:51], v[36:37]
	s_waitcnt lgkmcnt(1)
	v_mov_b32_e32 v47, v38
	s_waitcnt lgkmcnt(0)
	v_mov_b32_e32 v38, v43
	v_mov_b32_e32 v46, v42
	v_pk_mul_f32 v[38:39], v[32:33], v[38:39] op_sel_hi:[0,1]
	v_mov_b32_e32 v42, v44
	v_mov_b32_e32 v43, v40
	v_pk_fma_f32 v[30:31], v[30:31], v[46:47], v[38:39] op_sel_hi:[0,1,1]
	v_mov_b32_e32 v40, v45
	v_pk_fma_f32 v[30:31], v[50:51], v[42:43], v[30:31] op_sel_hi:[0,1,1]
	v_pk_fma_f32 v[30:31], v[76:77], v[40:41], v[30:31] op_sel_hi:[0,1,1]
	v_mov_b32_e32 v27, v34
	v_mov_b32_e32 v75, v35
	v_pk_add_f32 v[4:5], v[4:5], v[30:31]
	v_mul_f32_e32 v28, v50, v28
	v_mul_f32_e32 v30, v51, v29
	v_pk_add_f32 v[26:27], v[26:27], v[74:75]
	v_mov_b32_e32 v29, v36
	v_pk_add_f32 v[26:27], v[26:27], v[28:29]
	v_mov_b32_e32 v31, v37
	v_pk_add_f32 v[26:27], v[26:27], v[30:31]
	v_mov_b32_e32 v30, v92
	v_mov_b32_e32 v31, v93
	v_mov_b32_e32 v46, v94
	v_mov_b32_e32 v47, v95
	v_pk_add_f32 v[2:3], v[2:3], v[26:27]
	ds_read_b128 v[26:29], v10 offset:240
	ds_read_b128 v[34:37], v10 offset:256
	ds_read_b128 v[38:41], v10 offset:160
	ds_read_b128 v[42:45], v10 offset:144
	s_waitcnt lgkmcnt(1)
	v_mov_b32_e32 v49, v38
	s_waitcnt lgkmcnt(0)
	v_mov_b32_e32 v38, v43
	v_mov_b32_e32 v48, v42
	v_mov_b32_e32 v42, v44
	v_mov_b32_e32 v43, v40
	v_mov_b32_e32 v40, v45
	v_mul_f32_e32 v12, v30, v26
	v_mov_b32_e32 v32, v31
	v_pk_mul_f32 v[38:39], v[32:33], v[38:39] op_sel_hi:[0,1]
	v_pk_fma_f32 v[38:39], v[30:31], v[48:49], v[38:39] op_sel_hi:[0,1,1]
	v_pk_fma_f32 v[38:39], v[46:47], v[42:43], v[38:39] op_sel_hi:[0,1,1]
	v_mov_b32_e32 v48, v47
	v_pk_fma_f32 v[38:39], v[48:49], v[40:41], v[38:39] op_sel_hi:[0,1,1]
	v_pk_add_f32 v[6:7], v[6:7], v[38:39]
	ds_read_b128 v[38:41], v10 offset:192
	ds_read_b128 v[42:45], v10 offset:176
	v_mul_f32_e32 v26, v31, v27
	v_pk_mul_f32 v[34:35], v[30:31], v[34:35]
	v_pk_mul_f32 v[36:37], v[46:47], v[36:37]
	s_waitcnt lgkmcnt(1)
	v_mov_b32_e32 v51, v38
	s_waitcnt lgkmcnt(0)
	v_mov_b32_e32 v38, v43
	v_mov_b32_e32 v50, v42
	v_pk_mul_f32 v[38:39], v[32:33], v[38:39] op_sel_hi:[0,1]
	v_mov_b32_e32 v42, v44
	v_mov_b32_e32 v43, v40
	v_pk_fma_f32 v[38:39], v[30:31], v[50:51], v[38:39] op_sel_hi:[0,1,1]
	v_mov_b32_e32 v40, v45
	v_pk_fma_f32 v[38:39], v[46:47], v[42:43], v[38:39] op_sel_hi:[0,1,1]
	v_pk_fma_f32 v[38:39], v[48:49], v[40:41], v[38:39] op_sel_hi:[0,1,1]
	v_pk_add_f32 v[8:9], v[8:9], v[38:39]
	ds_read_b128 v[38:41], v10 offset:224
	ds_read_b128 v[42:45], v10 offset:208
	v_mov_b32_e32 v13, v34
	v_mov_b32_e32 v27, v35
	v_mul_f32_e32 v28, v46, v28
	s_waitcnt lgkmcnt(1)
	v_mov_b32_e32 v51, v38
	s_waitcnt lgkmcnt(0)
	v_mov_b32_e32 v38, v43
	v_mov_b32_e32 v50, v42
	v_pk_mul_f32 v[38:39], v[32:33], v[38:39] op_sel_hi:[0,1]
	v_mov_b32_e32 v42, v44
	v_mov_b32_e32 v43, v40
	v_pk_fma_f32 v[30:31], v[30:31], v[50:51], v[38:39] op_sel_hi:[0,1,1]
	v_mov_b32_e32 v40, v45
	v_pk_fma_f32 v[30:31], v[46:47], v[42:43], v[30:31] op_sel_hi:[0,1,1]
	v_pk_fma_f32 v[30:31], v[48:49], v[40:41], v[30:31] op_sel_hi:[0,1,1]
	v_pk_add_f32 v[4:5], v[4:5], v[30:31]
	v_mul_f32_e32 v30, v47, v29
	v_pk_add_f32 v[12:13], v[12:13], v[26:27]
	v_mov_b32_e32 v29, v36
	v_pk_add_f32 v[12:13], v[12:13], v[28:29]
	v_mov_b32_e32 v31, v37
	v_pk_add_f32 v[12:13], v[12:13], v[30:31]
	v_add_u32_e32 v10, 0x120, v10
	v_pk_add_f32 v[2:3], v[2:3], v[12:13]
	v_mov_b32_e32 v30, v96
	v_mov_b32_e32 v31, v97
	v_mov_b32_e32 v50, v98
	v_mov_b32_e32 v51, v99
	ds_read_b128 v[26:29], v10 offset:96
	ds_read_b128 v[34:37], v10 offset:112
	ds_read_b128 v[38:41], v10
	ds_read_b128 v[42:45], v10 offset:16
	ds_read_b128 v[46:49], v10 offset:32
	ds_read_b128 v[70:73], v10 offset:48
	s_add_u32 s4, s4, 0x200
	s_waitcnt lgkmcnt(0)
	v_mov_b32_e32 v76, v38
	v_mov_b32_e32 v77, v42
	v_mov_b32_e32 v42, v39
	v_mov_b32_e32 v38, v40
	v_mov_b32_e32 v39, v44
	v_mov_b32_e32 v44, v41
	s_addc_u32 s5, s5, 0
	v_mul_f32_e32 v26, v30, v26
	v_mov_b32_e32 v32, v31
	v_pk_mul_f32 v[40:41], v[32:33], v[42:43] op_sel_hi:[0,1]
	v_pk_fma_f32 v[40:41], v[30:31], v[76:77], v[40:41] op_sel_hi:[0,1,1]
	v_pk_fma_f32 v[38:39], v[50:51], v[38:39], v[40:41] op_sel_hi:[0,1,1]
	v_mov_b32_e32 v76, v51
	v_pk_fma_f32 v[38:39], v[76:77], v[44:45], v[38:39] op_sel_hi:[0,1,1]
	v_pk_add_f32 v[6:7], v[6:7], v[38:39]
	v_mov_b32_e32 v39, v70
	v_mov_b32_e32 v70, v47
	v_mov_b32_e32 v38, v46
	v_pk_mul_f32 v[42:43], v[32:33], v[70:71] op_sel_hi:[0,1]
	v_mov_b32_e32 v40, v48
	v_mov_b32_e32 v41, v72
	v_pk_fma_f32 v[38:39], v[30:31], v[38:39], v[42:43] op_sel_hi:[0,1,1]
	v_mov_b32_e32 v72, v49
	v_pk_fma_f32 v[38:39], v[50:51], v[40:41], v[38:39] op_sel_hi:[0,1,1]
	v_pk_fma_f32 v[38:39], v[76:77], v[72:73], v[38:39] op_sel_hi:[0,1,1]
	v_pk_add_f32 v[8:9], v[8:9], v[38:39]
	ds_read_b128 v[38:41], v10 offset:80
	ds_read_b128 v[42:45], v10 offset:64
	v_mul_f32_e32 v74, v31, v27
	v_pk_mul_f32 v[34:35], v[30:31], v[34:35]
	v_pk_mul_f32 v[36:37], v[50:51], v[36:37]
	s_waitcnt lgkmcnt(1)
; __device__ __forceinline__ void router_rows(const Params& p, char* smem, int l, int nrows) {
;     ...
;       for (int kg = 0; kg < 16; ++kg) {
;         const float w0 = wp[(kg * 4 + 0) * 16], w1 = wp[(kg * 4 + 1) * 16], w2 = wp[(kg * 4 + 2) * 16], w3 = wp[(kg * 4 + 3) * 16];
; #pragma unroll
;         for (int r = 0; r < 8; ++r) {
;           const float4 hv = *(const float4*)&hp[kg * 36 + r * 4];
;           acc[r] += hv.x * w0 + hv.y * w1 + hv.z * w2 + hv.w * w3;
;         }
;       }
	v_mov_b32_e32 v47, v38
	s_waitcnt lgkmcnt(0)
	v_mov_b32_e32 v38, v43
	v_mov_b32_e32 v46, v42
	v_pk_mul_f32 v[38:39], v[32:33], v[38:39] op_sel_hi:[0,1]
	v_mov_b32_e32 v42, v44
	v_mov_b32_e32 v43, v40
	v_pk_fma_f32 v[30:31], v[30:31], v[46:47], v[38:39] op_sel_hi:[0,1,1]
	v_mov_b32_e32 v40, v45
	v_pk_fma_f32 v[30:31], v[50:51], v[42:43], v[30:31] op_sel_hi:[0,1,1]
	v_pk_fma_f32 v[30:31], v[76:77], v[40:41], v[30:31] op_sel_hi:[0,1,1]
	v_mov_b32_e32 v27, v34
	v_mov_b32_e32 v75, v35
	v_pk_add_f32 v[4:5], v[4:5], v[30:31]
	v_mul_f32_e32 v28, v50, v28
	v_mul_f32_e32 v30, v51, v29
	v_pk_add_f32 v[26:27], v[26:27], v[74:75]
	v_mov_b32_e32 v29, v36
	v_pk_add_f32 v[26:27], v[26:27], v[28:29]
	v_mov_b32_e32 v31, v37
	v_pk_add_f32 v[26:27], v[26:27], v[30:31]
	v_mov_b32_e32 v30, v100
	v_mov_b32_e32 v31, v101
	v_mov_b32_e32 v46, v102
	v_mov_b32_e32 v47, v103
	v_pk_add_f32 v[2:3], v[2:3], v[26:27]
	ds_read_b128 v[26:29], v10 offset:240
	ds_read_b128 v[34:37], v10 offset:256
	ds_read_b128 v[38:41], v10 offset:160
	ds_read_b128 v[42:45], v10 offset:144
	s_waitcnt lgkmcnt(1)
	v_mov_b32_e32 v49, v38
	s_waitcnt lgkmcnt(0)
	v_mov_b32_e32 v38, v43
	v_mov_b32_e32 v48, v42
	v_mov_b32_e32 v42, v44
	v_mov_b32_e32 v43, v40
	v_mov_b32_e32 v40, v45
	v_mul_f32_e32 v12, v30, v26
	v_mov_b32_e32 v32, v31
	v_pk_mul_f32 v[38:39], v[32:33], v[38:39] op_sel_hi:[0,1]
	v_pk_fma_f32 v[38:39], v[30:31], v[48:49], v[38:39] op_sel_hi:[0,1,1]
	v_pk_fma_f32 v[38:39], v[46:47], v[42:43], v[38:39] op_sel_hi:[0,1,1]
	v_mov_b32_e32 v48, v47
	v_pk_fma_f32 v[38:39], v[48:49], v[40:41], v[38:39] op_sel_hi:[0,1,1]
	v_pk_add_f32 v[6:7], v[6:7], v[38:39]
	ds_read_b128 v[38:41], v10 offset:192
	ds_read_b128 v[42:45], v10 offset:176
	v_mul_f32_e32 v26, v31, v27
	v_pk_mul_f32 v[34:35], v[30:31], v[34:35]
	v_pk_mul_f32 v[36:37], v[46:47], v[36:37]
	s_waitcnt lgkmcnt(1)
	v_mov_b32_e32 v51, v38
	s_waitcnt lgkmcnt(0)
	v_mov_b32_e32 v38, v43
	v_mov_b32_e32 v50, v42
	v_pk_mul_f32 v[38:39], v[32:33], v[38:39] op_sel_hi:[0,1]
	v_mov_b32_e32 v42, v44
	v_mov_b32_e32 v43, v40
	v_pk_fma_f32 v[38:39], v[30:31], v[50:51], v[38:39] op_sel_hi:[0,1,1]
	v_mov_b32_e32 v40, v45
	v_pk_fma_f32 v[38:39], v[46:47], v[42:43], v[38:39] op_sel_hi:[0,1,1]
	v_pk_fma_f32 v[38:39], v[48:49], v[40:41], v[38:39] op_sel_hi:[0,1,1]
	v_pk_add_f32 v[8:9], v[8:9], v[38:39]
	ds_read_b128 v[38:41], v10 offset:224
	ds_read_b128 v[42:45], v10 offset:208
	v_mov_b32_e32 v13, v34
	v_mov_b32_e32 v27, v35
	v_mul_f32_e32 v28, v46, v28
	s_waitcnt lgkmcnt(1)
	v_mov_b32_e32 v51, v38
	s_waitcnt lgkmcnt(0)
	v_mov_b32_e32 v38, v43
	v_mov_b32_e32 v50, v42
	v_pk_mul_f32 v[38:39], v[32:33], v[38:39] op_sel_hi:[0,1]
	v_mov_b32_e32 v42, v44
	v_mov_b32_e32 v43, v40
	v_pk_fma_f32 v[30:31], v[30:31], v[50:51], v[38:39] op_sel_hi:[0,1,1]
	v_mov_b32_e32 v40, v45
	v_pk_fma_f32 v[30:31], v[46:47], v[42:43], v[30:31] op_sel_hi:[0,1,1]
	v_pk_fma_f32 v[30:31], v[48:49], v[40:41], v[30:31] op_sel_hi:[0,1,1]
	v_pk_add_f32 v[4:5], v[4:5], v[30:31]
	v_mul_f32_e32 v30, v47, v29
	v_pk_add_f32 v[12:13], v[12:13], v[26:27]
	v_mov_b32_e32 v29, v36
	v_pk_add_f32 v[12:13], v[12:13], v[28:29]
	v_mov_b32_e32 v31, v37
	v_pk_add_f32 v[12:13], v[12:13], v[30:31]
	v_add_u32_e32 v10, 0x120, v10
	v_pk_add_f32 v[2:3], v[2:3], v[12:13]
	v_mov_b32_e32 v30, v104
	v_mov_b32_e32 v31, v105
	v_mov_b32_e32 v50, v106
	v_mov_b32_e32 v51, v107
	ds_read_b128 v[26:29], v10 offset:96
	ds_read_b128 v[34:37], v10 offset:112
	ds_read_b128 v[38:41], v10
	ds_read_b128 v[42:45], v10 offset:16
	ds_read_b128 v[46:49], v10 offset:32
	ds_read_b128 v[70:73], v10 offset:48
	s_add_u32 s4, s4, 0x200
	s_waitcnt lgkmcnt(0)
	v_mov_b32_e32 v76, v38
	v_mov_b32_e32 v77, v42
	v_mov_b32_e32 v42, v39
	v_mov_b32_e32 v38, v40
	v_mov_b32_e32 v39, v44
	v_mov_b32_e32 v44, v41
	s_addc_u32 s5, s5, 0
	v_mul_f32_e32 v26, v30, v26
	v_mov_b32_e32 v32, v31
	v_pk_mul_f32 v[40:41], v[32:33], v[42:43] op_sel_hi:[0,1]
	v_pk_fma_f32 v[40:41], v[30:31], v[76:77], v[40:41] op_sel_hi:[0,1,1]
	v_pk_fma_f32 v[38:39], v[50:51], v[38:39], v[40:41] op_sel_hi:[0,1,1]
	v_mov_b32_e32 v76, v51
	v_pk_fma_f32 v[38:39], v[76:77], v[44:45], v[38:39] op_sel_hi:[0,1,1]
	v_pk_add_f32 v[6:7], v[6:7], v[38:39]
	v_mov_b32_e32 v39, v70
	v_mov_b32_e32 v70, v47
	v_mov_b32_e32 v38, v46
	v_pk_mul_f32 v[42:43], v[32:33], v[70:71] op_sel_hi:[0,1]
	v_mov_b32_e32 v40, v48
	v_mov_b32_e32 v41, v72
	v_pk_fma_f32 v[38:39], v[30:31], v[38:39], v[42:43] op_sel_hi:[0,1,1]
	v_mov_b32_e32 v72, v49
	v_pk_fma_f32 v[38:39], v[50:51], v[40:41], v[38:39] op_sel_hi:[0,1,1]
	v_pk_fma_f32 v[38:39], v[76:77], v[72:73], v[38:39] op_sel_hi:[0,1,1]
	v_pk_add_f32 v[8:9], v[8:9], v[38:39]
	ds_read_b128 v[38:41], v10 offset:80
	ds_read_b128 v[42:45], v10 offset:64
	v_mul_f32_e32 v74, v31, v27
	v_pk_mul_f32 v[34:35], v[30:31], v[34:35]
	v_pk_mul_f32 v[36:37], v[50:51], v[36:37]
	s_waitcnt lgkmcnt(1)
	v_mov_b32_e32 v47, v38
	s_waitcnt lgkmcnt(0)
	v_mov_b32_e32 v38, v43
	v_mov_b32_e32 v46, v42
	v_pk_mul_f32 v[38:39], v[32:33], v[38:39] op_sel_hi:[0,1]
	v_mov_b32_e32 v42, v44
	v_mov_b32_e32 v43, v40
	v_pk_fma_f32 v[30:31], v[30:31], v[46:47], v[38:39] op_sel_hi:[0,1,1]
	v_mov_b32_e32 v40, v45
	v_pk_fma_f32 v[30:31], v[50:51], v[42:43], v[30:31] op_sel_hi:[0,1,1]
	v_pk_fma_f32 v[30:31], v[76:77], v[40:41], v[30:31] op_sel_hi:[0,1,1]
	v_mov_b32_e32 v27, v34
	v_mov_b32_e32 v75, v35
	v_pk_add_f32 v[4:5], v[4:5], v[30:31]
	v_mul_f32_e32 v28, v50, v28
	v_mul_f32_e32 v30, v51, v29
	v_pk_add_f32 v[26:27], v[26:27], v[74:75]
	v_mov_b32_e32 v29, v36
	v_pk_add_f32 v[26:27], v[26:27], v[28:29]
	v_mov_b32_e32 v31, v37
	v_pk_add_f32 v[26:27], v[26:27], v[30:31]
	v_mov_b32_e32 v30, v108
	v_mov_b32_e32 v31, v109
	v_mov_b32_e32 v46, v110
	v_mov_b32_e32 v47, v111
	v_pk_add_f32 v[2:3], v[2:3], v[26:27]
	ds_read_b128 v[26:29], v10 offset:240
	ds_read_b128 v[34:37], v10 offset:256
	ds_read_b128 v[38:41], v10 offset:160
	ds_read_b128 v[42:45], v10 offset:144
	s_waitcnt lgkmcnt(1)
; __device__ __forceinline__ void router_rows(const Params& p, char* smem, int l, int nrows) {
;     ...
;       for (int kg = 0; kg < 16; ++kg) {
;         const float w0 = wp[(kg * 4 + 0) * 16], w1 = wp[(kg * 4 + 1) * 16], w2 = wp[(kg * 4 + 2) * 16], w3 = wp[(kg * 4 + 3) * 16];
; #pragma unroll
;         for (int r = 0; r < 8; ++r) {
;           const float4 hv = *(const float4*)&hp[kg * 36 + r * 4];
;           acc[r] += hv.x * w0 + hv.y * w1 + hv.z * w2 + hv.w * w3;
;         }
;       }
	v_mov_b32_e32 v49, v38
	s_waitcnt lgkmcnt(0)
	v_mov_b32_e32 v38, v43
	v_mov_b32_e32 v48, v42
	v_mov_b32_e32 v42, v44
	v_mov_b32_e32 v43, v40
	v_mov_b32_e32 v40, v45
	v_mul_f32_e32 v12, v30, v26
	v_mov_b32_e32 v32, v31
	v_pk_mul_f32 v[38:39], v[32:33], v[38:39] op_sel_hi:[0,1]
	v_pk_fma_f32 v[38:39], v[30:31], v[48:49], v[38:39] op_sel_hi:[0,1,1]
	v_pk_fma_f32 v[38:39], v[46:47], v[42:43], v[38:39] op_sel_hi:[0,1,1]
	v_mov_b32_e32 v48, v47
	v_pk_fma_f32 v[38:39], v[48:49], v[40:41], v[38:39] op_sel_hi:[0,1,1]
	v_pk_add_f32 v[6:7], v[6:7], v[38:39]
	ds_read_b128 v[38:41], v10 offset:192
	ds_read_b128 v[42:45], v10 offset:176
	v_mul_f32_e32 v26, v31, v27
	v_pk_mul_f32 v[34:35], v[30:31], v[34:35]
	v_pk_mul_f32 v[36:37], v[46:47], v[36:37]
	s_waitcnt lgkmcnt(1)
	v_mov_b32_e32 v51, v38
	s_waitcnt lgkmcnt(0)
	v_mov_b32_e32 v38, v43
	v_mov_b32_e32 v50, v42
	v_pk_mul_f32 v[38:39], v[32:33], v[38:39] op_sel_hi:[0,1]
	v_mov_b32_e32 v42, v44
	v_mov_b32_e32 v43, v40
	v_pk_fma_f32 v[38:39], v[30:31], v[50:51], v[38:39] op_sel_hi:[0,1,1]
	v_mov_b32_e32 v40, v45
	v_pk_fma_f32 v[38:39], v[46:47], v[42:43], v[38:39] op_sel_hi:[0,1,1]
	v_pk_fma_f32 v[38:39], v[48:49], v[40:41], v[38:39] op_sel_hi:[0,1,1]
	v_pk_add_f32 v[8:9], v[8:9], v[38:39]
	ds_read_b128 v[38:41], v10 offset:224
	ds_read_b128 v[42:45], v10 offset:208
	v_mov_b32_e32 v13, v34
	v_mov_b32_e32 v27, v35
	v_mul_f32_e32 v28, v46, v28
	s_waitcnt lgkmcnt(1)
	v_mov_b32_e32 v51, v38
	s_waitcnt lgkmcnt(0)
	v_mov_b32_e32 v38, v43
	v_mov_b32_e32 v50, v42
	v_pk_mul_f32 v[38:39], v[32:33], v[38:39] op_sel_hi:[0,1]
	v_mov_b32_e32 v42, v44
	v_mov_b32_e32 v43, v40
	v_pk_fma_f32 v[30:31], v[30:31], v[50:51], v[38:39] op_sel_hi:[0,1,1]
	v_mov_b32_e32 v40, v45
	v_pk_fma_f32 v[30:31], v[46:47], v[42:43], v[30:31] op_sel_hi:[0,1,1]
	v_pk_fma_f32 v[30:31], v[48:49], v[40:41], v[30:31] op_sel_hi:[0,1,1]
	v_pk_add_f32 v[4:5], v[4:5], v[30:31]
	v_mul_f32_e32 v30, v47, v29
	v_pk_add_f32 v[12:13], v[12:13], v[26:27]
	v_mov_b32_e32 v29, v36
	v_pk_add_f32 v[12:13], v[12:13], v[28:29]
	v_mov_b32_e32 v31, v37
	v_pk_add_f32 v[12:13], v[12:13], v[30:31]
	v_add_u32_e32 v10, 0x120, v10
	v_pk_add_f32 v[2:3], v[2:3], v[12:13]
	v_mov_b32_e32 v30, v112
	v_mov_b32_e32 v31, v113
	v_mov_b32_e32 v50, v114
	v_mov_b32_e32 v51, v115
	ds_read_b128 v[26:29], v10 offset:96
	ds_read_b128 v[34:37], v10 offset:112
	ds_read_b128 v[38:41], v10
	ds_read_b128 v[42:45], v10 offset:16
	ds_read_b128 v[46:49], v10 offset:32
	ds_read_b128 v[70:73], v10 offset:48
	s_add_u32 s4, s4, 0x200
	s_waitcnt lgkmcnt(0)
	v_mov_b32_e32 v76, v38
	v_mov_b32_e32 v77, v42
	v_mov_b32_e32 v42, v39
	v_mov_b32_e32 v38, v40
	v_mov_b32_e32 v39, v44
	v_mov_b32_e32 v44, v41
	s_addc_u32 s5, s5, 0
	v_mul_f32_e32 v26, v30, v26
	v_mov_b32_e32 v32, v31
	v_pk_mul_f32 v[40:41], v[32:33], v[42:43] op_sel_hi:[0,1]
	v_pk_fma_f32 v[40:41], v[30:31], v[76:77], v[40:41] op_sel_hi:[0,1,1]
	v_pk_fma_f32 v[38:39], v[50:51], v[38:39], v[40:41] op_sel_hi:[0,1,1]
	v_mov_b32_e32 v76, v51
	v_pk_fma_f32 v[38:39], v[76:77], v[44:45], v[38:39] op_sel_hi:[0,1,1]
	v_pk_add_f32 v[6:7], v[6:7], v[38:39]
	v_mov_b32_e32 v39, v70
	v_mov_b32_e32 v70, v47
	v_mov_b32_e32 v38, v46
	v_pk_mul_f32 v[42:43], v[32:33], v[70:71] op_sel_hi:[0,1]
	v_mov_b32_e32 v40, v48
	v_mov_b32_e32 v41, v72
	v_pk_fma_f32 v[38:39], v[30:31], v[38:39], v[42:43] op_sel_hi:[0,1,1]
	v_mov_b32_e32 v72, v49
	v_pk_fma_f32 v[38:39], v[50:51], v[40:41], v[38:39] op_sel_hi:[0,1,1]
	v_pk_fma_f32 v[38:39], v[76:77], v[72:73], v[38:39] op_sel_hi:[0,1,1]
	v_pk_add_f32 v[8:9], v[8:9], v[38:39]
	ds_read_b128 v[38:41], v10 offset:80
	ds_read_b128 v[42:45], v10 offset:64
	v_mul_f32_e32 v74, v31, v27
	v_pk_mul_f32 v[34:35], v[30:31], v[34:35]
	v_pk_mul_f32 v[36:37], v[50:51], v[36:37]
	s_waitcnt lgkmcnt(1)
	v_mov_b32_e32 v47, v38
	s_waitcnt lgkmcnt(0)
	v_mov_b32_e32 v38, v43
	v_mov_b32_e32 v46, v42
	v_pk_mul_f32 v[38:39], v[32:33], v[38:39] op_sel_hi:[0,1]
	v_mov_b32_e32 v42, v44
	v_mov_b32_e32 v43, v40
	v_pk_fma_f32 v[30:31], v[30:31], v[46:47], v[38:39] op_sel_hi:[0,1,1]
	v_mov_b32_e32 v40, v45
	v_pk_fma_f32 v[30:31], v[50:51], v[42:43], v[30:31] op_sel_hi:[0,1,1]
	v_pk_fma_f32 v[30:31], v[76:77], v[40:41], v[30:31] op_sel_hi:[0,1,1]
	v_mov_b32_e32 v27, v34
	v_mov_b32_e32 v75, v35
	v_pk_add_f32 v[4:5], v[4:5], v[30:31]
	v_mul_f32_e32 v28, v50, v28
	v_mul_f32_e32 v30, v51, v29
	v_pk_add_f32 v[26:27], v[26:27], v[74:75]
	v_mov_b32_e32 v29, v36
	v_pk_add_f32 v[26:27], v[26:27], v[28:29]
	v_mov_b32_e32 v31, v37
	v_pk_add_f32 v[26:27], v[26:27], v[30:31]
	v_mov_b32_e32 v30, v116
	v_mov_b32_e32 v31, v117
	v_mov_b32_e32 v46, v118
	v_mov_b32_e32 v47, v119
	v_pk_add_f32 v[2:3], v[2:3], v[26:27]
	ds_read_b128 v[26:29], v10 offset:240
	ds_read_b128 v[34:37], v10 offset:256
	ds_read_b128 v[38:41], v10 offset:160
	ds_read_b128 v[42:45], v10 offset:144
	s_waitcnt lgkmcnt(1)
	v_mov_b32_e32 v49, v38
	s_waitcnt lgkmcnt(0)
	v_mov_b32_e32 v38, v43
	v_mov_b32_e32 v48, v42
	v_mov_b32_e32 v42, v44
	v_mov_b32_e32 v43, v40
	v_mov_b32_e32 v40, v45
	v_mul_f32_e32 v12, v30, v26
	v_mov_b32_e32 v32, v31
	v_pk_mul_f32 v[38:39], v[32:33], v[38:39] op_sel_hi:[0,1]
	v_pk_fma_f32 v[38:39], v[30:31], v[48:49], v[38:39] op_sel_hi:[0,1,1]
	v_pk_fma_f32 v[38:39], v[46:47], v[42:43], v[38:39] op_sel_hi:[0,1,1]
	v_mov_b32_e32 v48, v47
	v_pk_fma_f32 v[38:39], v[48:49], v[40:41], v[38:39] op_sel_hi:[0,1,1]
	v_pk_add_f32 v[6:7], v[6:7], v[38:39]
	ds_read_b128 v[38:41], v10 offset:192
	ds_read_b128 v[42:45], v10 offset:176
	v_mul_f32_e32 v26, v31, v27
	v_pk_mul_f32 v[34:35], v[30:31], v[34:35]
	v_pk_mul_f32 v[36:37], v[46:47], v[36:37]
	s_waitcnt lgkmcnt(1)
	v_mov_b32_e32 v51, v38
	s_waitcnt lgkmcnt(0)
; __device__ __forceinline__ void router_rows(const Params& p, char* smem, int l, int nrows) {
;     ...
;       for (int kg = 0; kg < 16; ++kg) {
;         const float w0 = wp[(kg * 4 + 0) * 16], w1 = wp[(kg * 4 + 1) * 16], w2 = wp[(kg * 4 + 2) * 16], w3 = wp[(kg * 4 + 3) * 16];
; #pragma unroll
;         for (int r = 0; r < 8; ++r) {
;           const float4 hv = *(const float4*)&hp[kg * 36 + r * 4];
;           acc[r] += hv.x * w0 + hv.y * w1 + hv.z * w2 + hv.w * w3;
;         }
;       }
	v_mov_b32_e32 v38, v43
	v_mov_b32_e32 v50, v42
	v_pk_mul_f32 v[38:39], v[32:33], v[38:39] op_sel_hi:[0,1]
	v_mov_b32_e32 v42, v44
	v_mov_b32_e32 v43, v40
	v_pk_fma_f32 v[38:39], v[30:31], v[50:51], v[38:39] op_sel_hi:[0,1,1]
	v_mov_b32_e32 v40, v45
	v_pk_fma_f32 v[38:39], v[46:47], v[42:43], v[38:39] op_sel_hi:[0,1,1]
	v_pk_fma_f32 v[38:39], v[48:49], v[40:41], v[38:39] op_sel_hi:[0,1,1]
	v_pk_add_f32 v[8:9], v[8:9], v[38:39]
	ds_read_b128 v[38:41], v10 offset:224
	ds_read_b128 v[42:45], v10 offset:208
	v_mov_b32_e32 v13, v34
	v_mov_b32_e32 v27, v35
	v_mul_f32_e32 v28, v46, v28
	s_waitcnt lgkmcnt(1)
	v_mov_b32_e32 v51, v38
	s_waitcnt lgkmcnt(0)
	v_mov_b32_e32 v38, v43
	v_mov_b32_e32 v50, v42
	v_pk_mul_f32 v[38:39], v[32:33], v[38:39] op_sel_hi:[0,1]
	v_mov_b32_e32 v42, v44
	v_mov_b32_e32 v43, v40
	v_pk_fma_f32 v[30:31], v[30:31], v[50:51], v[38:39] op_sel_hi:[0,1,1]
	v_mov_b32_e32 v40, v45
	v_pk_fma_f32 v[30:31], v[46:47], v[42:43], v[30:31] op_sel_hi:[0,1,1]
	v_pk_fma_f32 v[30:31], v[48:49], v[40:41], v[30:31] op_sel_hi:[0,1,1]
	v_pk_add_f32 v[4:5], v[4:5], v[30:31]
	v_mul_f32_e32 v30, v47, v29
	v_pk_add_f32 v[12:13], v[12:13], v[26:27]
	v_mov_b32_e32 v29, v36
	v_pk_add_f32 v[12:13], v[12:13], v[28:29]
	v_mov_b32_e32 v31, v37
	v_pk_add_f32 v[12:13], v[12:13], v[30:31]
	v_add_u32_e32 v10, 0x120, v10
	v_pk_add_f32 v[2:3], v[2:3], v[12:13]
	v_mov_b32_e32 v30, v120
	v_mov_b32_e32 v31, v121
	v_mov_b32_e32 v50, v122
	v_mov_b32_e32 v51, v123
	ds_read_b128 v[26:29], v10 offset:96
	ds_read_b128 v[34:37], v10 offset:112
	ds_read_b128 v[38:41], v10
	ds_read_b128 v[42:45], v10 offset:16
	ds_read_b128 v[46:49], v10 offset:32
	ds_read_b128 v[70:73], v10 offset:48
	s_add_u32 s4, s4, 0x200
	s_waitcnt lgkmcnt(0)
	v_mov_b32_e32 v76, v38
	v_mov_b32_e32 v77, v42
	v_mov_b32_e32 v42, v39
	v_mov_b32_e32 v38, v40
	v_mov_b32_e32 v39, v44
	v_mov_b32_e32 v44, v41
	s_addc_u32 s5, s5, 0
	v_mul_f32_e32 v26, v30, v26
	v_mov_b32_e32 v32, v31
	v_pk_mul_f32 v[40:41], v[32:33], v[42:43] op_sel_hi:[0,1]
	v_pk_fma_f32 v[40:41], v[30:31], v[76:77], v[40:41] op_sel_hi:[0,1,1]
	v_pk_fma_f32 v[38:39], v[50:51], v[38:39], v[40:41] op_sel_hi:[0,1,1]
	v_mov_b32_e32 v76, v51
	v_pk_fma_f32 v[38:39], v[76:77], v[44:45], v[38:39] op_sel_hi:[0,1,1]
	v_pk_add_f32 v[6:7], v[6:7], v[38:39]
	v_mov_b32_e32 v39, v70
	v_mov_b32_e32 v70, v47
	v_mov_b32_e32 v38, v46
	v_pk_mul_f32 v[42:43], v[32:33], v[70:71] op_sel_hi:[0,1]
	v_mov_b32_e32 v40, v48
	v_mov_b32_e32 v41, v72
	v_pk_fma_f32 v[38:39], v[30:31], v[38:39], v[42:43] op_sel_hi:[0,1,1]
	v_mov_b32_e32 v72, v49
	v_pk_fma_f32 v[38:39], v[50:51], v[40:41], v[38:39] op_sel_hi:[0,1,1]
	v_pk_fma_f32 v[38:39], v[76:77], v[72:73], v[38:39] op_sel_hi:[0,1,1]
	v_pk_add_f32 v[8:9], v[8:9], v[38:39]
	ds_read_b128 v[38:41], v10 offset:80
	ds_read_b128 v[42:45], v10 offset:64
	v_mul_f32_e32 v74, v31, v27
	v_pk_mul_f32 v[34:35], v[30:31], v[34:35]
	v_pk_mul_f32 v[36:37], v[50:51], v[36:37]
	s_waitcnt lgkmcnt(1)
	v_mov_b32_e32 v47, v38
	s_waitcnt lgkmcnt(0)
	v_mov_b32_e32 v38, v43
	v_mov_b32_e32 v46, v42
	v_pk_mul_f32 v[38:39], v[32:33], v[38:39] op_sel_hi:[0,1]
	v_mov_b32_e32 v42, v44
	v_mov_b32_e32 v43, v40
	v_pk_fma_f32 v[30:31], v[30:31], v[46:47], v[38:39] op_sel_hi:[0,1,1]
	v_mov_b32_e32 v40, v45
	v_pk_fma_f32 v[30:31], v[50:51], v[42:43], v[30:31] op_sel_hi:[0,1,1]
	v_pk_fma_f32 v[30:31], v[76:77], v[40:41], v[30:31] op_sel_hi:[0,1,1]
	v_mov_b32_e32 v27, v34
	v_mov_b32_e32 v75, v35
	v_pk_add_f32 v[4:5], v[4:5], v[30:31]
	v_mul_f32_e32 v28, v50, v28
	v_mul_f32_e32 v30, v51, v29
	v_pk_add_f32 v[26:27], v[26:27], v[74:75]
	v_mov_b32_e32 v29, v36
	v_pk_add_f32 v[26:27], v[26:27], v[28:29]
	v_mov_b32_e32 v31, v37
	v_pk_add_f32 v[26:27], v[26:27], v[30:31]
	v_mov_b32_e32 v30, v124
	v_mov_b32_e32 v31, v125
	v_mov_b32_e32 v46, v126
	v_mov_b32_e32 v47, v127
	v_pk_add_f32 v[2:3], v[2:3], v[26:27]
	ds_read_b128 v[26:29], v10 offset:240
	ds_read_b128 v[34:37], v10 offset:256
	ds_read_b128 v[38:41], v10 offset:160
	ds_read_b128 v[42:45], v10 offset:144
	s_waitcnt lgkmcnt(1)
	v_mov_b32_e32 v49, v38
	s_waitcnt lgkmcnt(0)
	v_mov_b32_e32 v38, v43
	v_mov_b32_e32 v48, v42
	v_mov_b32_e32 v42, v44
	v_mov_b32_e32 v43, v40
	v_mov_b32_e32 v40, v45
	v_mul_f32_e32 v12, v30, v26
	v_mov_b32_e32 v32, v31
	v_pk_mul_f32 v[38:39], v[32:33], v[38:39] op_sel_hi:[0,1]
	v_pk_fma_f32 v[38:39], v[30:31], v[48:49], v[38:39] op_sel_hi:[0,1,1]
	v_pk_fma_f32 v[38:39], v[46:47], v[42:43], v[38:39] op_sel_hi:[0,1,1]
	v_mov_b32_e32 v48, v47
	v_pk_fma_f32 v[38:39], v[48:49], v[40:41], v[38:39] op_sel_hi:[0,1,1]
	v_pk_add_f32 v[6:7], v[6:7], v[38:39]
	ds_read_b128 v[38:41], v10 offset:192
	ds_read_b128 v[42:45], v10 offset:176
	v_mul_f32_e32 v26, v31, v27
	v_pk_mul_f32 v[34:35], v[30:31], v[34:35]
	v_pk_mul_f32 v[36:37], v[46:47], v[36:37]
	s_waitcnt lgkmcnt(1)
	v_mov_b32_e32 v51, v38
	s_waitcnt lgkmcnt(0)
	v_mov_b32_e32 v38, v43
	v_mov_b32_e32 v50, v42
	v_pk_mul_f32 v[38:39], v[32:33], v[38:39] op_sel_hi:[0,1]
	v_mov_b32_e32 v42, v44
	v_mov_b32_e32 v43, v40
	v_pk_fma_f32 v[38:39], v[30:31], v[50:51], v[38:39] op_sel_hi:[0,1,1]
	v_mov_b32_e32 v40, v45
	v_pk_fma_f32 v[38:39], v[46:47], v[42:43], v[38:39] op_sel_hi:[0,1,1]
	v_pk_fma_f32 v[38:39], v[48:49], v[40:41], v[38:39] op_sel_hi:[0,1,1]
	v_pk_add_f32 v[8:9], v[8:9], v[38:39]
	ds_read_b128 v[38:41], v10 offset:224
	ds_read_b128 v[42:45], v10 offset:208
	v_mov_b32_e32 v13, v34
	v_mov_b32_e32 v27, v35
	v_mul_f32_e32 v28, v46, v28
	s_waitcnt lgkmcnt(1)
	v_mov_b32_e32 v51, v38
	s_waitcnt lgkmcnt(0)
; __device__ __forceinline__ void router_rows(const Params& p, char* smem, int l, int nrows) {
;     ...
;       for (int kg = 0; kg < 16; ++kg) {
;         const float w0 = wp[(kg * 4 + 0) * 16], w1 = wp[(kg * 4 + 1) * 16], w2 = wp[(kg * 4 + 2) * 16], w3 = wp[(kg * 4 + 3) * 16];
; #pragma unroll
;         for (int r = 0; r < 8; ++r) {
;           const float4 hv = *(const float4*)&hp[kg * 36 + r * 4];
;           acc[r] += hv.x * w0 + hv.y * w1 + hv.z * w2 + hv.w * w3;
;         }
;       }
	v_mov_b32_e32 v38, v43
	v_mov_b32_e32 v50, v42
	v_pk_mul_f32 v[38:39], v[32:33], v[38:39] op_sel_hi:[0,1]
	v_mov_b32_e32 v42, v44
	v_mov_b32_e32 v43, v40
	v_pk_fma_f32 v[30:31], v[30:31], v[50:51], v[38:39] op_sel_hi:[0,1,1]
	v_mov_b32_e32 v40, v45
	v_pk_fma_f32 v[30:31], v[46:47], v[42:43], v[30:31] op_sel_hi:[0,1,1]
	v_pk_fma_f32 v[30:31], v[48:49], v[40:41], v[30:31] op_sel_hi:[0,1,1]
	v_pk_add_f32 v[4:5], v[4:5], v[30:31]
	v_mul_f32_e32 v30, v47, v29
	v_pk_add_f32 v[12:13], v[12:13], v[26:27]
	v_mov_b32_e32 v29, v36
	v_pk_add_f32 v[12:13], v[12:13], v[28:29]
	v_mov_b32_e32 v31, v37
	v_pk_add_f32 v[12:13], v[12:13], v[30:31]
	v_add_u32_e32 v10, 0x120, v10
	v_pk_add_f32 v[2:3], v[2:3], v[12:13]
	v_mov_b32_e32 v30, v128
	v_mov_b32_e32 v31, v129
	v_mov_b32_e32 v50, v130
	v_mov_b32_e32 v51, v131
	ds_read_b128 v[26:29], v10 offset:96
	ds_read_b128 v[34:37], v10 offset:112
	ds_read_b128 v[38:41], v10
	ds_read_b128 v[42:45], v10 offset:16
	ds_read_b128 v[46:49], v10 offset:32
	ds_read_b128 v[70:73], v10 offset:48
	s_add_u32 s4, s4, 0x200
	s_waitcnt lgkmcnt(0)
	v_mov_b32_e32 v76, v38
	v_mov_b32_e32 v77, v42
	v_mov_b32_e32 v42, v39
	v_mov_b32_e32 v38, v40
	v_mov_b32_e32 v39, v44
	v_mov_b32_e32 v44, v41
	s_addc_u32 s5, s5, 0
	v_mul_f32_e32 v26, v30, v26
	v_mov_b32_e32 v32, v31
	v_pk_mul_f32 v[40:41], v[32:33], v[42:43] op_sel_hi:[0,1]
	v_pk_fma_f32 v[40:41], v[30:31], v[76:77], v[40:41] op_sel_hi:[0,1,1]
	v_pk_fma_f32 v[38:39], v[50:51], v[38:39], v[40:41] op_sel_hi:[0,1,1]
	v_mov_b32_e32 v76, v51
	v_pk_fma_f32 v[38:39], v[76:77], v[44:45], v[38:39] op_sel_hi:[0,1,1]
	v_pk_add_f32 v[6:7], v[6:7], v[38:39]
	v_mov_b32_e32 v39, v70
	v_mov_b32_e32 v70, v47
	v_mov_b32_e32 v38, v46
	v_pk_mul_f32 v[42:43], v[32:33], v[70:71] op_sel_hi:[0,1]
	v_mov_b32_e32 v40, v48
	v_mov_b32_e32 v41, v72
	v_pk_fma_f32 v[38:39], v[30:31], v[38:39], v[42:43] op_sel_hi:[0,1,1]
	v_mov_b32_e32 v72, v49
	v_pk_fma_f32 v[38:39], v[50:51], v[40:41], v[38:39] op_sel_hi:[0,1,1]
	v_pk_fma_f32 v[38:39], v[76:77], v[72:73], v[38:39] op_sel_hi:[0,1,1]
	v_pk_add_f32 v[8:9], v[8:9], v[38:39]
	ds_read_b128 v[38:41], v10 offset:80
	ds_read_b128 v[42:45], v10 offset:64
	v_mul_f32_e32 v74, v31, v27
	v_pk_mul_f32 v[34:35], v[30:31], v[34:35]
	v_pk_mul_f32 v[36:37], v[50:51], v[36:37]
	s_waitcnt lgkmcnt(1)
	v_mov_b32_e32 v47, v38
	s_waitcnt lgkmcnt(0)
	v_mov_b32_e32 v38, v43
	v_mov_b32_e32 v46, v42
	v_pk_mul_f32 v[38:39], v[32:33], v[38:39] op_sel_hi:[0,1]
	v_mov_b32_e32 v42, v44
	v_mov_b32_e32 v43, v40
	v_pk_fma_f32 v[30:31], v[30:31], v[46:47], v[38:39] op_sel_hi:[0,1,1]
	v_mov_b32_e32 v40, v45
	v_pk_fma_f32 v[30:31], v[50:51], v[42:43], v[30:31] op_sel_hi:[0,1,1]
	v_pk_fma_f32 v[30:31], v[76:77], v[40:41], v[30:31] op_sel_hi:[0,1,1]
	v_mov_b32_e32 v27, v34
	v_mov_b32_e32 v75, v35
	v_pk_add_f32 v[4:5], v[4:5], v[30:31]
	v_mul_f32_e32 v28, v50, v28
	v_mul_f32_e32 v30, v51, v29
	v_pk_add_f32 v[26:27], v[26:27], v[74:75]
	v_mov_b32_e32 v29, v36
	v_pk_add_f32 v[26:27], v[26:27], v[28:29]
	v_mov_b32_e32 v31, v37
	v_pk_add_f32 v[26:27], v[26:27], v[30:31]
	v_mov_b32_e32 v30, v132
	v_mov_b32_e32 v31, v133
	v_mov_b32_e32 v46, v134
	v_mov_b32_e32 v47, v135
	v_pk_add_f32 v[2:3], v[2:3], v[26:27]
	ds_read_b128 v[26:29], v10 offset:240
	ds_read_b128 v[34:37], v10 offset:256
	ds_read_b128 v[38:41], v10 offset:160
	ds_read_b128 v[42:45], v10 offset:144
	s_waitcnt lgkmcnt(1)
	v_mov_b32_e32 v49, v38
	s_waitcnt lgkmcnt(0)
	v_mov_b32_e32 v38, v43
	v_mov_b32_e32 v48, v42
	v_mov_b32_e32 v42, v44
	v_mov_b32_e32 v43, v40
	v_mov_b32_e32 v40, v45
	v_mul_f32_e32 v12, v30, v26
	v_mov_b32_e32 v32, v31
	v_pk_mul_f32 v[38:39], v[32:33], v[38:39] op_sel_hi:[0,1]
	v_pk_fma_f32 v[38:39], v[30:31], v[48:49], v[38:39] op_sel_hi:[0,1,1]
	v_pk_fma_f32 v[38:39], v[46:47], v[42:43], v[38:39] op_sel_hi:[0,1,1]
	v_mov_b32_e32 v48, v47
	v_pk_fma_f32 v[38:39], v[48:49], v[40:41], v[38:39] op_sel_hi:[0,1,1]
	v_pk_add_f32 v[6:7], v[6:7], v[38:39]
	ds_read_b128 v[38:41], v10 offset:192
	ds_read_b128 v[42:45], v10 offset:176
	v_mul_f32_e32 v26, v31, v27
	v_pk_mul_f32 v[34:35], v[30:31], v[34:35]
	v_pk_mul_f32 v[36:37], v[46:47], v[36:37]
	s_waitcnt lgkmcnt(1)
	v_mov_b32_e32 v51, v38
	s_waitcnt lgkmcnt(0)
	v_mov_b32_e32 v38, v43
	v_mov_b32_e32 v50, v42
	v_pk_mul_f32 v[38:39], v[32:33], v[38:39] op_sel_hi:[0,1]
	v_mov_b32_e32 v42, v44
	v_mov_b32_e32 v43, v40
	v_pk_fma_f32 v[38:39], v[30:31], v[50:51], v[38:39] op_sel_hi:[0,1,1]
	v_mov_b32_e32 v40, v45
	v_pk_fma_f32 v[38:39], v[46:47], v[42:43], v[38:39] op_sel_hi:[0,1,1]
	v_pk_fma_f32 v[38:39], v[48:49], v[40:41], v[38:39] op_sel_hi:[0,1,1]
	v_pk_add_f32 v[8:9], v[8:9], v[38:39]
	ds_read_b128 v[38:41], v10 offset:224
	ds_read_b128 v[42:45], v10 offset:208
	v_mov_b32_e32 v13, v34
	v_mov_b32_e32 v27, v35
	v_mul_f32_e32 v28, v46, v28
	s_waitcnt lgkmcnt(1)
	v_mov_b32_e32 v51, v38
	s_waitcnt lgkmcnt(0)
	v_mov_b32_e32 v38, v43
	v_mov_b32_e32 v50, v42
	v_pk_mul_f32 v[38:39], v[32:33], v[38:39] op_sel_hi:[0,1]
	v_mov_b32_e32 v42, v44
	v_mov_b32_e32 v43, v40
	v_pk_fma_f32 v[30:31], v[30:31], v[50:51], v[38:39] op_sel_hi:[0,1,1]
	v_mov_b32_e32 v40, v45
	v_pk_fma_f32 v[30:31], v[46:47], v[42:43], v[30:31] op_sel_hi:[0,1,1]
	v_pk_fma_f32 v[30:31], v[48:49], v[40:41], v[30:31] op_sel_hi:[0,1,1]
	v_pk_add_f32 v[4:5], v[4:5], v[30:31]
	v_mul_f32_e32 v30, v47, v29
	v_pk_add_f32 v[12:13], v[12:13], v[26:27]
	v_mov_b32_e32 v29, v36
	v_pk_add_f32 v[12:13], v[12:13], v[28:29]
	v_mov_b32_e32 v31, v37
	v_pk_add_f32 v[12:13], v[12:13], v[30:31]
	v_add_u32_e32 v10, 0x120, v10
	v_pk_add_f32 v[2:3], v[2:3], v[12:13]
	v_mov_b32_e32 v30, v136
	v_mov_b32_e32 v31, v137
	v_mov_b32_e32 v50, v138
	v_mov_b32_e32 v51, v139
	ds_read_b128 v[26:29], v10 offset:96
	ds_read_b128 v[34:37], v10 offset:112
	ds_read_b128 v[38:41], v10
	ds_read_b128 v[42:45], v10 offset:16
	ds_read_b128 v[46:49], v10 offset:32
	ds_read_b128 v[70:73], v10 offset:48
	s_add_u32 s4, s4, 0x200
	s_waitcnt lgkmcnt(0)
; __device__ __forceinline__ void router_rows(const Params& p, char* smem, int l, int nrows) {
;     ...
;       for (int kg = 0; kg < 16; ++kg) {
;         const float w0 = wp[(kg * 4 + 0) * 16], w1 = wp[(kg * 4 + 1) * 16], w2 = wp[(kg * 4 + 2) * 16], w3 = wp[(kg * 4 + 3) * 16];
; #pragma unroll
;         for (int r = 0; r < 8; ++r) {
;           const float4 hv = *(const float4*)&hp[kg * 36 + r * 4];
;           acc[r] += hv.x * w0 + hv.y * w1 + hv.z * w2 + hv.w * w3;
;         }
;       }
; #pragma unroll
;       for (int r = 0; r < 8; ++r) {
;         acc[r] += __shfl_xor(acc[r], 16);
;         acc[r] += __shfl_xor(acc[r], 32);
;       }
;       if (lane < 16) {
; #pragma unroll
;         for (int r = 0; r < 8; ++r) red[(wid * 8 + r) * 16 + lane] = acc[r];
;       }
	v_mov_b32_e32 v76, v38
	v_mov_b32_e32 v77, v42
	v_mov_b32_e32 v42, v39
	v_mov_b32_e32 v38, v40
	v_mov_b32_e32 v39, v44
	v_mov_b32_e32 v44, v41
	s_addc_u32 s5, s5, 0
	v_mul_f32_e32 v26, v30, v26
	v_mov_b32_e32 v32, v31
	v_pk_mul_f32 v[40:41], v[32:33], v[42:43] op_sel_hi:[0,1]
	v_pk_fma_f32 v[40:41], v[30:31], v[76:77], v[40:41] op_sel_hi:[0,1,1]
	v_pk_fma_f32 v[38:39], v[50:51], v[38:39], v[40:41] op_sel_hi:[0,1,1]
	v_mov_b32_e32 v76, v51
	v_pk_fma_f32 v[38:39], v[76:77], v[44:45], v[38:39] op_sel_hi:[0,1,1]
	v_pk_add_f32 v[6:7], v[6:7], v[38:39]
	v_mov_b32_e32 v39, v70
	v_mov_b32_e32 v70, v47
	v_mov_b32_e32 v38, v46
	v_pk_mul_f32 v[42:43], v[32:33], v[70:71] op_sel_hi:[0,1]
	v_mov_b32_e32 v40, v48
	v_mov_b32_e32 v41, v72
	v_pk_fma_f32 v[38:39], v[30:31], v[38:39], v[42:43] op_sel_hi:[0,1,1]
	v_mov_b32_e32 v72, v49
	v_pk_fma_f32 v[38:39], v[50:51], v[40:41], v[38:39] op_sel_hi:[0,1,1]
	v_pk_fma_f32 v[38:39], v[76:77], v[72:73], v[38:39] op_sel_hi:[0,1,1]
	v_pk_add_f32 v[8:9], v[8:9], v[38:39]
	ds_read_b128 v[38:41], v10 offset:80
	ds_read_b128 v[42:45], v10 offset:64
	v_mul_f32_e32 v74, v31, v27
	v_pk_mul_f32 v[34:35], v[30:31], v[34:35]
	v_pk_mul_f32 v[36:37], v[50:51], v[36:37]
	s_waitcnt lgkmcnt(1)
	v_mov_b32_e32 v47, v38
	s_waitcnt lgkmcnt(0)
	v_mov_b32_e32 v38, v43
	v_mov_b32_e32 v46, v42
	v_pk_mul_f32 v[38:39], v[32:33], v[38:39] op_sel_hi:[0,1]
	v_mov_b32_e32 v42, v44
	v_mov_b32_e32 v43, v40
	v_pk_fma_f32 v[30:31], v[30:31], v[46:47], v[38:39] op_sel_hi:[0,1,1]
	v_mov_b32_e32 v40, v45
	v_pk_fma_f32 v[30:31], v[50:51], v[42:43], v[30:31] op_sel_hi:[0,1,1]
	v_pk_fma_f32 v[30:31], v[76:77], v[40:41], v[30:31] op_sel_hi:[0,1,1]
	v_mov_b32_e32 v27, v34
	v_mov_b32_e32 v75, v35
	v_pk_add_f32 v[4:5], v[4:5], v[30:31]
	v_mul_f32_e32 v28, v50, v28
	v_mul_f32_e32 v30, v51, v29
	v_pk_add_f32 v[26:27], v[26:27], v[74:75]
	v_mov_b32_e32 v29, v36
	v_pk_add_f32 v[26:27], v[26:27], v[28:29]
	v_mov_b32_e32 v31, v37
	v_pk_add_f32 v[26:27], v[26:27], v[30:31]
	v_mov_b32_e32 v30, v140
	v_mov_b32_e32 v31, v141
	v_mov_b32_e32 v46, v142
	v_mov_b32_e32 v47, v143
	v_pk_add_f32 v[2:3], v[2:3], v[26:27]
	ds_read_b128 v[26:29], v10 offset:240
	ds_read_b128 v[34:37], v10 offset:256
	ds_read_b128 v[38:41], v10 offset:160
	ds_read_b128 v[42:45], v10 offset:144
	s_waitcnt lgkmcnt(1)
	v_mov_b32_e32 v49, v38
	s_waitcnt lgkmcnt(0)
	v_mov_b32_e32 v38, v43
	v_mov_b32_e32 v48, v42
	v_mov_b32_e32 v42, v44
	v_mov_b32_e32 v43, v40
	v_mov_b32_e32 v40, v45
	v_mul_f32_e32 v12, v30, v26
	v_mov_b32_e32 v32, v31
	v_pk_mul_f32 v[38:39], v[32:33], v[38:39] op_sel_hi:[0,1]
	v_pk_fma_f32 v[38:39], v[30:31], v[48:49], v[38:39] op_sel_hi:[0,1,1]
	v_pk_fma_f32 v[38:39], v[46:47], v[42:43], v[38:39] op_sel_hi:[0,1,1]
	v_mov_b32_e32 v48, v47
	v_pk_fma_f32 v[38:39], v[48:49], v[40:41], v[38:39] op_sel_hi:[0,1,1]
	v_pk_add_f32 v[6:7], v[6:7], v[38:39]
	ds_read_b128 v[38:41], v10 offset:192
	ds_read_b128 v[42:45], v10 offset:176
	v_mul_f32_e32 v26, v31, v27
	v_pk_mul_f32 v[34:35], v[30:31], v[34:35]
	v_pk_mul_f32 v[36:37], v[46:47], v[36:37]
	s_waitcnt lgkmcnt(1)
	v_mov_b32_e32 v51, v38
	s_waitcnt lgkmcnt(0)
	v_mov_b32_e32 v38, v43
	v_mov_b32_e32 v50, v42
	v_pk_mul_f32 v[38:39], v[32:33], v[38:39] op_sel_hi:[0,1]
	v_mov_b32_e32 v42, v44
	v_mov_b32_e32 v43, v40
	v_pk_fma_f32 v[38:39], v[30:31], v[50:51], v[38:39] op_sel_hi:[0,1,1]
	v_mov_b32_e32 v40, v45
	v_pk_fma_f32 v[38:39], v[46:47], v[42:43], v[38:39] op_sel_hi:[0,1,1]
	v_pk_fma_f32 v[38:39], v[48:49], v[40:41], v[38:39] op_sel_hi:[0,1,1]
	v_pk_add_f32 v[8:9], v[8:9], v[38:39]
	ds_read_b128 v[38:41], v10 offset:224
	ds_read_b128 v[42:45], v10 offset:208
	v_mov_b32_e32 v13, v34
	v_mov_b32_e32 v27, v35
	v_mul_f32_e32 v28, v46, v28
	s_waitcnt lgkmcnt(1)
	v_mov_b32_e32 v51, v38
	s_waitcnt lgkmcnt(0)
	v_mov_b32_e32 v38, v43
	v_mov_b32_e32 v50, v42
	v_pk_mul_f32 v[38:39], v[32:33], v[38:39] op_sel_hi:[0,1]
	v_mov_b32_e32 v42, v44
	v_mov_b32_e32 v43, v40
	v_pk_fma_f32 v[30:31], v[30:31], v[50:51], v[38:39] op_sel_hi:[0,1,1]
	v_mov_b32_e32 v40, v45
	v_pk_fma_f32 v[30:31], v[46:47], v[42:43], v[30:31] op_sel_hi:[0,1,1]
	v_pk_fma_f32 v[30:31], v[48:49], v[40:41], v[30:31] op_sel_hi:[0,1,1]
	v_pk_add_f32 v[4:5], v[4:5], v[30:31]
	v_mul_f32_e32 v30, v47, v29
	v_pk_add_f32 v[12:13], v[12:13], v[26:27]
	v_mov_b32_e32 v29, v36
	v_pk_add_f32 v[12:13], v[12:13], v[28:29]
	v_mov_b32_e32 v31, v37
	v_pk_add_f32 v[12:13], v[12:13], v[30:31]
	v_add_u32_e32 v10, 0x120, v10
	v_pk_add_f32 v[2:3], v[2:3], v[12:13]
	ds_bpermute_b32 v10, v53, v6
	ds_bpermute_b32 v11, v53, v7
	ds_bpermute_b32 v12, v53, v8
	ds_bpermute_b32 v13, v53, v9
	ds_bpermute_b32 v26, v53, v4
	ds_bpermute_b32 v27, v53, v5
	ds_bpermute_b32 v28, v53, v2
	ds_bpermute_b32 v29, v53, v3
	s_waitcnt lgkmcnt(7)
	v_add_f32_e32 v6, v6, v10
	s_waitcnt lgkmcnt(6)
	v_add_f32_e32 v10, v7, v11
	s_waitcnt lgkmcnt(5)
	v_add_f32_e32 v8, v8, v12
	s_waitcnt lgkmcnt(4)
	v_add_f32_e32 v9, v9, v13
	s_waitcnt lgkmcnt(3)
	v_add_f32_e32 v4, v4, v26
	s_waitcnt lgkmcnt(2)
	v_add_f32_e32 v5, v5, v27
	s_waitcnt lgkmcnt(1)
	v_add_f32_e32 v2, v2, v28
	s_waitcnt lgkmcnt(0)
	v_add_f32_e32 v3, v3, v29
	ds_bpermute_b32 v7, v52, v6
	ds_bpermute_b32 v11, v52, v10
	ds_bpermute_b32 v12, v52, v8
	ds_bpermute_b32 v13, v52, v9
	ds_bpermute_b32 v26, v52, v4
	ds_bpermute_b32 v27, v52, v5
	ds_bpermute_b32 v28, v52, v2
	ds_bpermute_b32 v29, v52, v3
	s_and_saveexec_b64 s[4:5], s[38:39]
	s_cbranch_execz .LBB0_1274
	s_waitcnt lgkmcnt(6)
	v_add_f32_e32 v10, v10, v11
	v_add_f32_e32 v6, v6, v7
	v_add_u32_e32 v7, 0x9000, v69
	s_waitcnt lgkmcnt(0)
	v_add_f32_e32 v3, v3, v29
	v_add_f32_e32 v2, v2, v28
	v_add_f32_e32 v5, v5, v27
	v_add_f32_e32 v4, v4, v26
	v_add_f32_e32 v9, v9, v13
	v_add_f32_e32 v8, v8, v12
	ds_write2_b32 v7, v6, v10 offset1:16
	ds_write2_b32 v7, v8, v9 offset0:32 offset1:48
	ds_write2_b32 v7, v4, v5 offset0:64 offset1:80
	ds_write2_b32 v7, v2, v3 offset0:96 offset1:112
